# QK-norm epilogue: per-lane norm gains loaded once per tile instead of per row group behind vmcnt(0)
# baseline (speedup 1.0000x reference)
;     __device__ __forceinline__ void operator()(const f32x4 (&acc)[2][2][4][2], const pg8::Unit& u, int wr, int wc, int fr, int fq, LAS unsigned char* sp) const {
;     ...
;                     const int row = row0 + ai * 128 + m * 16; const float s = rsl[ai * 128 + m * 16];
;                     f32x4 v[2][2];
; #pragma unroll
;                     for (int bj = 0; bj < 2; ++bj)
; #pragma unroll
;                         for (int n = 0; n < 2; ++n) v[bj][n] = acc[ai][bj][m][n] * s;
;                     if (act == 3) {
;                         float q = 0.f;
; #pragma unroll
;                         for (int bj = 0; bj < 2; ++bj)
; #pragma unroll
;                             for (int n = 0; n < 2; ++n) q += (v[bj][n][0] * v[bj][n][0] + v[bj][n][1] * v[bj][n][1]) + (v[bj][n][2] * v[bj][n][2] + v[bj][n][3] * v[bj][n][3]);
;                         q += __shfl_xor(q, 16); q += __shfl_xor(q, 32);
;                         const float ri = rsqrtf(q * (1.f / 64.f) + EPS) * osc;
; #pragma unroll
;                         for (int bj = 0; bj < 2; ++bj)
; #pragma unroll
;                             for (int n = 0; n < 2; ++n) { const f32x4 g = *(const f32x4*)(gn + 32 * bj + 8 * fq + 4 * n); v[bj][n] = v[bj][n] * g * ri; }
.LBB0_351:
	v_mov_b32_e32 v161, v1
	s_andn2_b64 vcc, exec, s[8:9]
	v_lshl_add_u64 v[166:167], s[68:69], 0, v[160:161]
	s_cbranch_vccnz .LBB0_353
	v_pk_mul_f32 v[114:115], v[176:177], v[176:177]
	v_pk_mul_f32 v[116:117], v[178:179], v[178:179]
	v_mul_f32_e32 v0, v174, v174
	v_pk_mov_b32 v[118:119], v[116:117], v[114:115] op_sel:[1,0]
	v_mov_b32_e32 v117, v115
	v_pk_add_f32 v[114:115], v[118:119], v[116:117]
	v_pk_mul_f32 v[116:117], v[180:181], v[180:181]
	v_pk_mul_f32 v[118:119], v[182:183], v[182:183]
	v_pk_add_f32 v[114:115], v[114:115], v[114:115] op_sel_hi:[0,1]
	v_pk_mov_b32 v[120:121], v[118:119], v[116:117] op_sel:[1,0]
	v_mov_b32_e32 v119, v117
	v_pk_add_f32 v[116:117], v[120:121], v[118:119]
	v_pk_fma_f32 v[118:119], v[174:175], v[174:175], v[0:1] op_sel_hi:[1,1,0]
	v_mul_f32_e32 v0, v172, v172
	v_pk_add_f32 v[116:117], v[116:117], v[116:117] op_sel_hi:[0,1]
	v_pk_fma_f32 v[120:121], v[172:173], v[172:173], v[0:1] op_sel_hi:[1,1,0]
	v_mul_f32_e32 v118, v170, v170
	v_mul_f32_e32 v120, v171, v171
	v_mul_f32_e32 v114, v168, v168
	v_mul_f32_e32 v116, v169, v169
	v_pk_add_f32 v[118:119], v[118:119], v[120:121]
	v_pk_add_f32 v[114:115], v[114:115], v[116:117]
	s_nop 0
	v_pk_add_f32 v[114:115], v[118:119], v[114:115]
	s_nop 0
	v_add_f32_e32 v0, v114, v115
	v_and_b32_e32 v115, 64, v187
	v_xor_b32_e32 v114, 16, v187
	v_add_u32_e32 v115, 64, v115
	v_cmp_lt_i32_e32 vcc, v114, v115
	s_nop 1
	v_cndmask_b32_e32 v114, v187, v114, vcc
	v_lshlrev_b32_e32 v114, 2, v114
	ds_bpermute_b32 v114, v114, v0
	s_waitcnt lgkmcnt(0)
	v_add_f32_e32 v0, v0, v114
	v_xor_b32_e32 v114, 32, v187
	v_cmp_lt_i32_e32 vcc, v114, v115
	s_nop 1
	v_cndmask_b32_e32 v114, v187, v114, vcc
	v_lshlrev_b32_e32 v114, 2, v114
	ds_bpermute_b32 v114, v114, v0
	s_waitcnt lgkmcnt(0)
	v_add_f32_e32 v0, v0, v114
	v_fmamk_f32 v0, v0, 0x3c800000, v184
	v_cmp_gt_f32_e32 vcc, s74, v0
	v_mul_f32_e32 v114, 0x4b800000, v0
	s_nop 0
	v_cndmask_b32_e32 v0, v0, v114, vcc
	v_rsq_f32_e32 v0, v0
	s_nop 0
	v_mul_f32_e32 v114, 0x45800000, v0
	v_cndmask_b32_e32 v0, v0, v114, vcc
	global_load_dwordx4 v[212:215], v[166:167], off offset:16
	global_load_dwordx4 v[208:211], v[166:167], off
	global_load_dwordx4 v[220:223], v[166:167], off offset:144
	global_load_dwordx4 v[216:219], v[166:167], off offset:128
	v_mul_f32_e32 v0, v164, v0
	s_waitcnt vmcnt(0)
	v_pk_mul_f32 v[120:121], v[180:181], v[214:215]
	v_pk_mul_f32 v[116:117], v[176:177], v[210:211]
	v_pk_mul_f32 v[114:115], v[178:179], v[208:209]
	v_pk_mul_f32 v[118:119], v[182:183], v[212:213]
	v_pk_mul_f32 v[128:129], v[172:173], v[218:219]
	v_pk_mul_f32 v[126:127], v[174:175], v[216:217]
	v_pk_mul_f32 v[124:125], v[168:169], v[222:223]
	v_pk_mul_f32 v[122:123], v[170:171], v[220:221]
	v_pk_mul_f32 v[116:117], v[116:117], v[0:1] op_sel_hi:[1,0]
	v_pk_mul_f32 v[114:115], v[114:115], v[0:1] op_sel_hi:[1,0]
	v_pk_mul_f32 v[120:121], v[120:121], v[0:1] op_sel_hi:[1,0]
	v_pk_mul_f32 v[118:119], v[118:119], v[0:1] op_sel_hi:[1,0]
	v_pk_mul_f32 v[128:129], v[128:129], v[0:1] op_sel_hi:[1,0]
	v_pk_mul_f32 v[126:127], v[126:127], v[0:1] op_sel_hi:[1,0]
	v_pk_mul_f32 v[124:125], v[124:125], v[0:1] op_sel_hi:[1,0]
	v_pk_mul_f32 v[122:123], v[122:123], v[0:1] op_sel_hi:[1,0]

;     __device__ __forceinline__ void operator()(const f32x4 (&acc)[2][2][4][2], const pg8::Unit& u, int wr, int wc, int fr, int fq, LAS unsigned char* sp) const {
;     ...
;                     const int row = row0 + ai * 128 + m * 16; const float s = rsl[ai * 128 + m * 16];
;                     f32x4 v[2][2];
; #pragma unroll
;                     for (int bj = 0; bj < 2; ++bj)
; #pragma unroll
;                         for (int n = 0; n < 2; ++n) v[bj][n] = acc[ai][bj][m][n] * s;
;                     if (act == 3) {
;                         float q = 0.f;
; #pragma unroll
;                         for (int bj = 0; bj < 2; ++bj)
; #pragma unroll
;                             for (int n = 0; n < 2; ++n) q += (v[bj][n][0] * v[bj][n][0] + v[bj][n][1] * v[bj][n][1]) + (v[bj][n][2] * v[bj][n][2] + v[bj][n][3] * v[bj][n][3]);
;                         q += __shfl_xor(q, 16); q += __shfl_xor(q, 32);
;                         const float ri = rsqrtf(q * (1.f / 64.f) + EPS) * osc;
; #pragma unroll
;                         for (int bj = 0; bj < 2; ++bj)
; #pragma unroll
;                             for (int n = 0; n < 2; ++n) { const f32x4 g = *(const f32x4*)(gn + 32 * bj + 8 * fq + 4 * n); v[bj][n] = v[bj][n] * g * ri; }
.LBB0_355:
	s_andn2_b64 vcc, exec, s[64:65]
	s_cbranch_vccnz .LBB0_357
	v_pk_mul_f32 v[98:99], v[122:123], v[122:123]
	v_pk_mul_f32 v[100:101], v[124:125], v[124:125]
	v_mul_f32_e32 v0, v120, v120
	v_pk_mov_b32 v[102:103], v[100:101], v[98:99] op_sel:[1,0]
	v_mov_b32_e32 v101, v99
	v_pk_add_f32 v[98:99], v[102:103], v[100:101]
	v_pk_mul_f32 v[100:101], v[126:127], v[126:127]
	v_pk_mul_f32 v[102:103], v[128:129], v[128:129]
	v_pk_add_f32 v[98:99], v[98:99], v[98:99] op_sel_hi:[0,1]
	v_pk_mov_b32 v[104:105], v[102:103], v[100:101] op_sel:[1,0]
	v_mov_b32_e32 v103, v101
	v_pk_add_f32 v[100:101], v[104:105], v[102:103]
	v_pk_fma_f32 v[102:103], v[120:121], v[120:121], v[0:1] op_sel_hi:[1,1,0]
	v_mul_f32_e32 v0, v118, v118
	v_pk_add_f32 v[100:101], v[100:101], v[100:101] op_sel_hi:[0,1]
	v_pk_fma_f32 v[104:105], v[118:119], v[118:119], v[0:1] op_sel_hi:[1,1,0]
	v_mul_f32_e32 v102, v116, v116
	v_mul_f32_e32 v104, v117, v117
	v_mul_f32_e32 v98, v114, v114
	v_mul_f32_e32 v100, v115, v115
	v_pk_add_f32 v[102:103], v[102:103], v[104:105]
	v_pk_add_f32 v[98:99], v[98:99], v[100:101]
	s_nop 0
	v_pk_add_f32 v[98:99], v[102:103], v[98:99]
	s_nop 0
	v_add_f32_e32 v0, v98, v99
	v_and_b32_e32 v99, 64, v187
	v_xor_b32_e32 v98, 16, v187
	v_add_u32_e32 v99, 64, v99
	v_cmp_lt_i32_e32 vcc, v98, v99
	s_nop 1
	v_cndmask_b32_e32 v98, v187, v98, vcc
	v_lshlrev_b32_e32 v98, 2, v98
	ds_bpermute_b32 v98, v98, v0
	s_waitcnt lgkmcnt(0)
	v_add_f32_e32 v0, v0, v98
	v_xor_b32_e32 v98, 32, v187
	v_cmp_lt_i32_e32 vcc, v98, v99
	s_nop 1
	v_cndmask_b32_e32 v98, v187, v98, vcc
	v_lshlrev_b32_e32 v98, 2, v98
	ds_bpermute_b32 v98, v98, v0
	s_waitcnt lgkmcnt(0)
	v_add_f32_e32 v0, v0, v98
	v_fmamk_f32 v0, v0, 0x3c800000, v184
	v_cmp_gt_f32_e32 vcc, s74, v0
	v_mul_f32_e32 v98, 0x4b800000, v0
	s_nop 0
	v_cndmask_b32_e32 v0, v0, v98, vcc
	v_rsq_f32_e32 v0, v0
	s_nop 0
	v_mul_f32_e32 v98, 0x45800000, v0
	v_cndmask_b32_e32 v0, v0, v98, vcc
	v_mul_f32_e32 v0, v164, v0
	v_pk_mul_f32 v[104:105], v[126:127], v[214:215]
	v_pk_mul_f32 v[100:101], v[122:123], v[210:211]
	v_pk_mul_f32 v[98:99], v[124:125], v[208:209]
	v_pk_mul_f32 v[102:103], v[128:129], v[212:213]
	v_pk_mul_f32 v[112:113], v[118:119], v[218:219]
	v_pk_mul_f32 v[110:111], v[120:121], v[216:217]
	v_pk_mul_f32 v[108:109], v[114:115], v[222:223]
	v_pk_mul_f32 v[106:107], v[116:117], v[220:221]
	v_pk_mul_f32 v[100:101], v[100:101], v[0:1] op_sel_hi:[1,0]
	v_pk_mul_f32 v[98:99], v[98:99], v[0:1] op_sel_hi:[1,0]
	v_pk_mul_f32 v[104:105], v[104:105], v[0:1] op_sel_hi:[1,0]
	v_pk_mul_f32 v[102:103], v[102:103], v[0:1] op_sel_hi:[1,0]
	v_pk_mul_f32 v[112:113], v[112:113], v[0:1] op_sel_hi:[1,0]
	v_pk_mul_f32 v[110:111], v[110:111], v[0:1] op_sel_hi:[1,0]
	v_pk_mul_f32 v[108:109], v[108:109], v[0:1] op_sel_hi:[1,0]
	v_pk_mul_f32 v[106:107], v[106:107], v[0:1] op_sel_hi:[1,0]

;     __device__ __forceinline__ void operator()(const f32x4 (&acc)[2][2][4][2], const pg8::Unit& u, int wr, int wc, int fr, int fq, LAS unsigned char* sp) const {
;     ...
;                     const int row = row0 + ai * 128 + m * 16; const float s = rsl[ai * 128 + m * 16];
;                     f32x4 v[2][2];
; #pragma unroll
;                     for (int bj = 0; bj < 2; ++bj)
; #pragma unroll
;                         for (int n = 0; n < 2; ++n) v[bj][n] = acc[ai][bj][m][n] * s;
;                     if (act == 3) {
;                         float q = 0.f;
; #pragma unroll
;                         for (int bj = 0; bj < 2; ++bj)
; #pragma unroll
;                             for (int n = 0; n < 2; ++n) q += (v[bj][n][0] * v[bj][n][0] + v[bj][n][1] * v[bj][n][1]) + (v[bj][n][2] * v[bj][n][2] + v[bj][n][3] * v[bj][n][3]);
;                         q += __shfl_xor(q, 16); q += __shfl_xor(q, 32);
;                         const float ri = rsqrtf(q * (1.f / 64.f) + EPS) * osc;
; #pragma unroll
;                         for (int bj = 0; bj < 2; ++bj)
; #pragma unroll
;                             for (int n = 0; n < 2; ++n) { const f32x4 g = *(const f32x4*)(gn + 32 * bj + 8 * fq + 4 * n); v[bj][n] = v[bj][n] * g * ri; }
.LBB0_359:
	s_andn2_b64 vcc, exec, s[64:65]
	s_cbranch_vccnz .LBB0_361
	v_pk_mul_f32 v[82:83], v[106:107], v[106:107]
	v_pk_mul_f32 v[84:85], v[108:109], v[108:109]
	v_mul_f32_e32 v0, v104, v104
	v_pk_mov_b32 v[86:87], v[84:85], v[82:83] op_sel:[1,0]
	v_mov_b32_e32 v85, v83
	v_pk_add_f32 v[82:83], v[86:87], v[84:85]
	v_pk_mul_f32 v[84:85], v[110:111], v[110:111]
	v_pk_mul_f32 v[86:87], v[112:113], v[112:113]
	v_pk_add_f32 v[82:83], v[82:83], v[82:83] op_sel_hi:[0,1]
	v_pk_mov_b32 v[88:89], v[86:87], v[84:85] op_sel:[1,0]
	v_mov_b32_e32 v87, v85
	v_pk_add_f32 v[84:85], v[88:89], v[86:87]
	v_pk_fma_f32 v[86:87], v[104:105], v[104:105], v[0:1] op_sel_hi:[1,1,0]
	v_mul_f32_e32 v0, v102, v102
	v_pk_add_f32 v[84:85], v[84:85], v[84:85] op_sel_hi:[0,1]
	v_pk_fma_f32 v[88:89], v[102:103], v[102:103], v[0:1] op_sel_hi:[1,1,0]
	v_mul_f32_e32 v86, v100, v100
	v_mul_f32_e32 v88, v101, v101
	v_mul_f32_e32 v82, v98, v98
	v_mul_f32_e32 v84, v99, v99
	v_pk_add_f32 v[86:87], v[86:87], v[88:89]
	v_pk_add_f32 v[82:83], v[82:83], v[84:85]
	s_nop 0
	v_pk_add_f32 v[82:83], v[86:87], v[82:83]
	s_nop 0
	v_add_f32_e32 v0, v82, v83
	v_and_b32_e32 v83, 64, v187
	v_xor_b32_e32 v82, 16, v187
	v_add_u32_e32 v83, 64, v83
	v_cmp_lt_i32_e32 vcc, v82, v83
	s_nop 1
	v_cndmask_b32_e32 v82, v187, v82, vcc
	v_lshlrev_b32_e32 v82, 2, v82
	ds_bpermute_b32 v82, v82, v0
	s_waitcnt lgkmcnt(0)
	v_add_f32_e32 v0, v0, v82
	v_xor_b32_e32 v82, 32, v187
	v_cmp_lt_i32_e32 vcc, v82, v83
	s_nop 1
	v_cndmask_b32_e32 v82, v187, v82, vcc
	v_lshlrev_b32_e32 v82, 2, v82
	ds_bpermute_b32 v82, v82, v0
	s_waitcnt lgkmcnt(0)
	v_add_f32_e32 v0, v0, v82
	v_fmamk_f32 v0, v0, 0x3c800000, v184
	v_cmp_gt_f32_e32 vcc, s74, v0
	v_mul_f32_e32 v82, 0x4b800000, v0
	s_nop 0
	v_cndmask_b32_e32 v0, v0, v82, vcc
	v_rsq_f32_e32 v0, v0
	s_nop 0
	v_mul_f32_e32 v82, 0x45800000, v0
	v_cndmask_b32_e32 v0, v0, v82, vcc
	v_mul_f32_e32 v0, v164, v0
	v_pk_mul_f32 v[88:89], v[110:111], v[214:215]
	v_pk_mul_f32 v[84:85], v[106:107], v[210:211]
	v_pk_mul_f32 v[82:83], v[108:109], v[208:209]
	v_pk_mul_f32 v[86:87], v[112:113], v[212:213]
	v_pk_mul_f32 v[96:97], v[102:103], v[218:219]
	v_pk_mul_f32 v[94:95], v[104:105], v[216:217]
	v_pk_mul_f32 v[92:93], v[98:99], v[222:223]
	v_pk_mul_f32 v[90:91], v[100:101], v[220:221]
	v_pk_mul_f32 v[84:85], v[84:85], v[0:1] op_sel_hi:[1,0]
	v_pk_mul_f32 v[82:83], v[82:83], v[0:1] op_sel_hi:[1,0]
	v_pk_mul_f32 v[88:89], v[88:89], v[0:1] op_sel_hi:[1,0]
	v_pk_mul_f32 v[86:87], v[86:87], v[0:1] op_sel_hi:[1,0]
	v_pk_mul_f32 v[96:97], v[96:97], v[0:1] op_sel_hi:[1,0]
	v_pk_mul_f32 v[94:95], v[94:95], v[0:1] op_sel_hi:[1,0]
	v_pk_mul_f32 v[92:93], v[92:93], v[0:1] op_sel_hi:[1,0]
	v_pk_mul_f32 v[90:91], v[90:91], v[0:1] op_sel_hi:[1,0]

;     __device__ __forceinline__ void operator()(const f32x4 (&acc)[2][2][4][2], const pg8::Unit& u, int wr, int wc, int fr, int fq, LAS unsigned char* sp) const {
;     ...
;                     const int row = row0 + ai * 128 + m * 16; const float s = rsl[ai * 128 + m * 16];
;                     f32x4 v[2][2];
; #pragma unroll
;                     for (int bj = 0; bj < 2; ++bj)
; #pragma unroll
;                         for (int n = 0; n < 2; ++n) v[bj][n] = acc[ai][bj][m][n] * s;
;                     if (act == 3) {
;                         float q = 0.f;
; #pragma unroll
;                         for (int bj = 0; bj < 2; ++bj)
; #pragma unroll
;                             for (int n = 0; n < 2; ++n) q += (v[bj][n][0] * v[bj][n][0] + v[bj][n][1] * v[bj][n][1]) + (v[bj][n][2] * v[bj][n][2] + v[bj][n][3] * v[bj][n][3]);
;                         q += __shfl_xor(q, 16); q += __shfl_xor(q, 32);
;                         const float ri = rsqrtf(q * (1.f / 64.f) + EPS) * osc;
; #pragma unroll
;                         for (int bj = 0; bj < 2; ++bj)
; #pragma unroll
;                             for (int n = 0; n < 2; ++n) { const f32x4 g = *(const f32x4*)(gn + 32 * bj + 8 * fq + 4 * n); v[bj][n] = v[bj][n] * g * ri; }
.LBB0_363:
	s_andn2_b64 vcc, exec, s[64:65]
	s_cbranch_vccnz .LBB0_365
	v_pk_mul_f32 v[66:67], v[90:91], v[90:91]
	v_pk_mul_f32 v[68:69], v[92:93], v[92:93]
	v_mul_f32_e32 v0, v88, v88
	v_pk_mov_b32 v[70:71], v[68:69], v[66:67] op_sel:[1,0]
	v_mov_b32_e32 v69, v67
	v_pk_add_f32 v[66:67], v[70:71], v[68:69]
	v_pk_mul_f32 v[68:69], v[94:95], v[94:95]
	v_pk_mul_f32 v[70:71], v[96:97], v[96:97]
	v_pk_add_f32 v[66:67], v[66:67], v[66:67] op_sel_hi:[0,1]
	v_pk_mov_b32 v[72:73], v[70:71], v[68:69] op_sel:[1,0]
	v_mov_b32_e32 v71, v69
	v_pk_add_f32 v[68:69], v[72:73], v[70:71]
	v_pk_fma_f32 v[70:71], v[88:89], v[88:89], v[0:1] op_sel_hi:[1,1,0]
	v_mul_f32_e32 v0, v86, v86
	v_pk_add_f32 v[68:69], v[68:69], v[68:69] op_sel_hi:[0,1]
	v_pk_fma_f32 v[72:73], v[86:87], v[86:87], v[0:1] op_sel_hi:[1,1,0]
	v_mul_f32_e32 v70, v84, v84
	v_mul_f32_e32 v72, v85, v85
	v_mul_f32_e32 v66, v82, v82
	v_mul_f32_e32 v68, v83, v83
	v_pk_add_f32 v[70:71], v[70:71], v[72:73]
	v_pk_add_f32 v[66:67], v[66:67], v[68:69]
	s_nop 0
	v_pk_add_f32 v[66:67], v[70:71], v[66:67]
	s_nop 0
	v_add_f32_e32 v0, v66, v67
	v_and_b32_e32 v67, 64, v187
	v_xor_b32_e32 v66, 16, v187
	v_add_u32_e32 v67, 64, v67
	v_cmp_lt_i32_e32 vcc, v66, v67
	s_nop 1
	v_cndmask_b32_e32 v66, v187, v66, vcc
	v_lshlrev_b32_e32 v66, 2, v66
	ds_bpermute_b32 v66, v66, v0
	s_waitcnt lgkmcnt(0)
	v_add_f32_e32 v0, v0, v66
	v_xor_b32_e32 v66, 32, v187
	v_cmp_lt_i32_e32 vcc, v66, v67
	s_nop 1
	v_cndmask_b32_e32 v66, v187, v66, vcc
	v_lshlrev_b32_e32 v66, 2, v66
	ds_bpermute_b32 v66, v66, v0
	s_waitcnt lgkmcnt(0)
	v_add_f32_e32 v0, v0, v66
	v_fmamk_f32 v0, v0, 0x3c800000, v184
	v_cmp_gt_f32_e32 vcc, s74, v0
	v_mul_f32_e32 v66, 0x4b800000, v0
	s_nop 0
	v_cndmask_b32_e32 v0, v0, v66, vcc
	v_rsq_f32_e32 v0, v0
	s_nop 0
	v_mul_f32_e32 v66, 0x45800000, v0
	v_cndmask_b32_e32 v0, v0, v66, vcc
	v_mul_f32_e32 v0, v164, v0
	v_pk_mul_f32 v[72:73], v[94:95], v[214:215]
	v_pk_mul_f32 v[68:69], v[90:91], v[210:211]
	v_pk_mul_f32 v[66:67], v[92:93], v[208:209]
	v_pk_mul_f32 v[70:71], v[96:97], v[212:213]
	v_pk_mul_f32 v[80:81], v[86:87], v[218:219]
	v_pk_mul_f32 v[78:79], v[88:89], v[216:217]
	v_pk_mul_f32 v[76:77], v[82:83], v[222:223]
	v_pk_mul_f32 v[74:75], v[84:85], v[220:221]
	v_pk_mul_f32 v[68:69], v[68:69], v[0:1] op_sel_hi:[1,0]
	v_pk_mul_f32 v[66:67], v[66:67], v[0:1] op_sel_hi:[1,0]
	v_pk_mul_f32 v[72:73], v[72:73], v[0:1] op_sel_hi:[1,0]
	v_pk_mul_f32 v[70:71], v[70:71], v[0:1] op_sel_hi:[1,0]
	v_pk_mul_f32 v[80:81], v[80:81], v[0:1] op_sel_hi:[1,0]
	v_pk_mul_f32 v[78:79], v[78:79], v[0:1] op_sel_hi:[1,0]
	v_pk_mul_f32 v[76:77], v[76:77], v[0:1] op_sel_hi:[1,0]
	v_pk_mul_f32 v[74:75], v[74:75], v[0:1] op_sel_hi:[1,0]

;     __device__ __forceinline__ void operator()(const f32x4 (&acc)[2][2][4][2], const pg8::Unit& u, int wr, int wc, int fr, int fq, LAS unsigned char* sp) const {
;     ...
;                     const int row = row0 + ai * 128 + m * 16; const float s = rsl[ai * 128 + m * 16];
;                     f32x4 v[2][2];
; #pragma unroll
;                     for (int bj = 0; bj < 2; ++bj)
; #pragma unroll
;                         for (int n = 0; n < 2; ++n) v[bj][n] = acc[ai][bj][m][n] * s;
;                     if (act == 3) {
;                         float q = 0.f;
; #pragma unroll
;                         for (int bj = 0; bj < 2; ++bj)
; #pragma unroll
;                             for (int n = 0; n < 2; ++n) q += (v[bj][n][0] * v[bj][n][0] + v[bj][n][1] * v[bj][n][1]) + (v[bj][n][2] * v[bj][n][2] + v[bj][n][3] * v[bj][n][3]);
;                         q += __shfl_xor(q, 16); q += __shfl_xor(q, 32);
;                         const float ri = rsqrtf(q * (1.f / 64.f) + EPS) * osc;
; #pragma unroll
;                         for (int bj = 0; bj < 2; ++bj)
; #pragma unroll
;                             for (int n = 0; n < 2; ++n) { const f32x4 g = *(const f32x4*)(gn + 32 * bj + 8 * fq + 4 * n); v[bj][n] = v[bj][n] * g * ri; }
.LBB0_367:
	s_andn2_b64 vcc, exec, s[64:65]
	s_cbranch_vccnz .LBB0_369
	v_pk_mul_f32 v[50:51], v[74:75], v[74:75]
	v_pk_mul_f32 v[52:53], v[76:77], v[76:77]
	v_mul_f32_e32 v0, v72, v72
	v_pk_mov_b32 v[54:55], v[52:53], v[50:51] op_sel:[1,0]
	v_mov_b32_e32 v53, v51
	v_pk_add_f32 v[50:51], v[54:55], v[52:53]
	v_pk_mul_f32 v[52:53], v[78:79], v[78:79]
	v_pk_mul_f32 v[54:55], v[80:81], v[80:81]
	v_pk_add_f32 v[50:51], v[50:51], v[50:51] op_sel_hi:[0,1]
	v_pk_mov_b32 v[56:57], v[54:55], v[52:53] op_sel:[1,0]
	v_mov_b32_e32 v55, v53
	v_pk_add_f32 v[52:53], v[56:57], v[54:55]
	v_pk_fma_f32 v[54:55], v[72:73], v[72:73], v[0:1] op_sel_hi:[1,1,0]
	v_mul_f32_e32 v0, v70, v70
	v_pk_add_f32 v[52:53], v[52:53], v[52:53] op_sel_hi:[0,1]
	v_pk_fma_f32 v[56:57], v[70:71], v[70:71], v[0:1] op_sel_hi:[1,1,0]
	v_mul_f32_e32 v54, v68, v68
	v_mul_f32_e32 v56, v69, v69
	v_mul_f32_e32 v50, v66, v66
	v_mul_f32_e32 v52, v67, v67
	v_pk_add_f32 v[54:55], v[54:55], v[56:57]
	v_pk_add_f32 v[50:51], v[50:51], v[52:53]
	s_nop 0
	v_pk_add_f32 v[50:51], v[54:55], v[50:51]
	s_nop 0
	v_add_f32_e32 v0, v50, v51
	v_and_b32_e32 v51, 64, v187
	v_xor_b32_e32 v50, 16, v187
	v_add_u32_e32 v51, 64, v51
	v_cmp_lt_i32_e32 vcc, v50, v51
	s_nop 1
	v_cndmask_b32_e32 v50, v187, v50, vcc
	v_lshlrev_b32_e32 v50, 2, v50
	ds_bpermute_b32 v50, v50, v0
	s_waitcnt lgkmcnt(0)
	v_add_f32_e32 v0, v0, v50
	v_xor_b32_e32 v50, 32, v187
	v_cmp_lt_i32_e32 vcc, v50, v51
	s_nop 1
	v_cndmask_b32_e32 v50, v187, v50, vcc
	v_lshlrev_b32_e32 v50, 2, v50
	ds_bpermute_b32 v50, v50, v0
	s_waitcnt lgkmcnt(0)
	v_add_f32_e32 v0, v0, v50
	v_fmamk_f32 v0, v0, 0x3c800000, v184
	v_cmp_gt_f32_e32 vcc, s74, v0
	v_mul_f32_e32 v50, 0x4b800000, v0
	s_nop 0
	v_cndmask_b32_e32 v0, v0, v50, vcc
	v_rsq_f32_e32 v0, v0
	s_nop 0
	v_mul_f32_e32 v50, 0x45800000, v0
	v_cndmask_b32_e32 v0, v0, v50, vcc
	v_mul_f32_e32 v0, v164, v0
	v_pk_mul_f32 v[56:57], v[78:79], v[214:215]
	v_pk_mul_f32 v[52:53], v[74:75], v[210:211]
	v_pk_mul_f32 v[50:51], v[76:77], v[208:209]
	v_pk_mul_f32 v[54:55], v[80:81], v[212:213]
	v_pk_mul_f32 v[64:65], v[70:71], v[218:219]
	v_pk_mul_f32 v[62:63], v[72:73], v[216:217]
	v_pk_mul_f32 v[60:61], v[66:67], v[222:223]
	v_pk_mul_f32 v[58:59], v[68:69], v[220:221]
	v_pk_mul_f32 v[52:53], v[52:53], v[0:1] op_sel_hi:[1,0]
	v_pk_mul_f32 v[50:51], v[50:51], v[0:1] op_sel_hi:[1,0]
	v_pk_mul_f32 v[56:57], v[56:57], v[0:1] op_sel_hi:[1,0]
	v_pk_mul_f32 v[54:55], v[54:55], v[0:1] op_sel_hi:[1,0]
	v_pk_mul_f32 v[64:65], v[64:65], v[0:1] op_sel_hi:[1,0]
	v_pk_mul_f32 v[62:63], v[62:63], v[0:1] op_sel_hi:[1,0]
	v_pk_mul_f32 v[60:61], v[60:61], v[0:1] op_sel_hi:[1,0]
	v_pk_mul_f32 v[58:59], v[58:59], v[0:1] op_sel_hi:[1,0]

;     __device__ __forceinline__ void operator()(const f32x4 (&acc)[2][2][4][2], const pg8::Unit& u, int wr, int wc, int fr, int fq, LAS unsigned char* sp) const {
;     ...
;                     const int row = row0 + ai * 128 + m * 16; const float s = rsl[ai * 128 + m * 16];
;                     f32x4 v[2][2];
; #pragma unroll
;                     for (int bj = 0; bj < 2; ++bj)
; #pragma unroll
;                         for (int n = 0; n < 2; ++n) v[bj][n] = acc[ai][bj][m][n] * s;
;                     if (act == 3) {
;                         float q = 0.f;
; #pragma unroll
;                         for (int bj = 0; bj < 2; ++bj)
; #pragma unroll
;                             for (int n = 0; n < 2; ++n) q += (v[bj][n][0] * v[bj][n][0] + v[bj][n][1] * v[bj][n][1]) + (v[bj][n][2] * v[bj][n][2] + v[bj][n][3] * v[bj][n][3]);
;                         q += __shfl_xor(q, 16); q += __shfl_xor(q, 32);
;                         const float ri = rsqrtf(q * (1.f / 64.f) + EPS) * osc;
; #pragma unroll
;                         for (int bj = 0; bj < 2; ++bj)
; #pragma unroll
;                             for (int n = 0; n < 2; ++n) { const f32x4 g = *(const f32x4*)(gn + 32 * bj + 8 * fq + 4 * n); v[bj][n] = v[bj][n] * g * ri; }
.LBB0_371:
	s_andn2_b64 vcc, exec, s[64:65]
	s_cbranch_vccnz .LBB0_373
	v_pk_mul_f32 v[34:35], v[58:59], v[58:59]
	v_pk_mul_f32 v[36:37], v[60:61], v[60:61]
	v_mul_f32_e32 v0, v56, v56
	v_pk_mov_b32 v[38:39], v[36:37], v[34:35] op_sel:[1,0]
	v_mov_b32_e32 v37, v35
	v_pk_add_f32 v[34:35], v[38:39], v[36:37]
	v_pk_mul_f32 v[36:37], v[62:63], v[62:63]
	v_pk_mul_f32 v[38:39], v[64:65], v[64:65]
	v_pk_add_f32 v[34:35], v[34:35], v[34:35] op_sel_hi:[0,1]
	v_pk_mov_b32 v[40:41], v[38:39], v[36:37] op_sel:[1,0]
	v_mov_b32_e32 v39, v37
	v_pk_add_f32 v[36:37], v[40:41], v[38:39]
	v_pk_fma_f32 v[38:39], v[56:57], v[56:57], v[0:1] op_sel_hi:[1,1,0]
	v_mul_f32_e32 v0, v54, v54
	v_pk_add_f32 v[36:37], v[36:37], v[36:37] op_sel_hi:[0,1]
	v_pk_fma_f32 v[40:41], v[54:55], v[54:55], v[0:1] op_sel_hi:[1,1,0]
	v_mul_f32_e32 v38, v52, v52
	v_mul_f32_e32 v40, v53, v53
	v_mul_f32_e32 v34, v50, v50
	v_mul_f32_e32 v36, v51, v51
	v_pk_add_f32 v[38:39], v[38:39], v[40:41]
	v_pk_add_f32 v[34:35], v[34:35], v[36:37]
	s_nop 0
	v_pk_add_f32 v[34:35], v[38:39], v[34:35]
	s_nop 0
	v_add_f32_e32 v0, v34, v35
	v_and_b32_e32 v35, 64, v187
	v_xor_b32_e32 v34, 16, v187
	v_add_u32_e32 v35, 64, v35
	v_cmp_lt_i32_e32 vcc, v34, v35
	s_nop 1
	v_cndmask_b32_e32 v34, v187, v34, vcc
	v_lshlrev_b32_e32 v34, 2, v34
	ds_bpermute_b32 v34, v34, v0
	s_waitcnt lgkmcnt(0)
	v_add_f32_e32 v0, v0, v34
	v_xor_b32_e32 v34, 32, v187
	v_cmp_lt_i32_e32 vcc, v34, v35
	s_nop 1
	v_cndmask_b32_e32 v34, v187, v34, vcc
	v_lshlrev_b32_e32 v34, 2, v34
	ds_bpermute_b32 v34, v34, v0
	s_waitcnt lgkmcnt(0)
	v_add_f32_e32 v0, v0, v34
	v_fmamk_f32 v0, v0, 0x3c800000, v184
	v_cmp_gt_f32_e32 vcc, s74, v0
	v_mul_f32_e32 v34, 0x4b800000, v0
	s_nop 0
	v_cndmask_b32_e32 v0, v0, v34, vcc
	v_rsq_f32_e32 v0, v0
	s_nop 0
	v_mul_f32_e32 v34, 0x45800000, v0
	v_cndmask_b32_e32 v0, v0, v34, vcc
	v_mul_f32_e32 v0, v164, v0
	v_pk_mul_f32 v[40:41], v[62:63], v[214:215]
	v_pk_mul_f32 v[36:37], v[58:59], v[210:211]
	v_pk_mul_f32 v[34:35], v[60:61], v[208:209]
	v_pk_mul_f32 v[38:39], v[64:65], v[212:213]
	v_pk_mul_f32 v[48:49], v[54:55], v[218:219]
	v_pk_mul_f32 v[46:47], v[56:57], v[216:217]
	v_pk_mul_f32 v[44:45], v[50:51], v[222:223]
	v_pk_mul_f32 v[42:43], v[52:53], v[220:221]
	v_pk_mul_f32 v[36:37], v[36:37], v[0:1] op_sel_hi:[1,0]
	v_pk_mul_f32 v[34:35], v[34:35], v[0:1] op_sel_hi:[1,0]
	v_pk_mul_f32 v[40:41], v[40:41], v[0:1] op_sel_hi:[1,0]
	v_pk_mul_f32 v[38:39], v[38:39], v[0:1] op_sel_hi:[1,0]
	v_pk_mul_f32 v[48:49], v[48:49], v[0:1] op_sel_hi:[1,0]
	v_pk_mul_f32 v[46:47], v[46:47], v[0:1] op_sel_hi:[1,0]
	v_pk_mul_f32 v[44:45], v[44:45], v[0:1] op_sel_hi:[1,0]
	v_pk_mul_f32 v[42:43], v[42:43], v[0:1] op_sel_hi:[1,0]

;     __device__ __forceinline__ void operator()(const f32x4 (&acc)[2][2][4][2], const pg8::Unit& u, int wr, int wc, int fr, int fq, LAS unsigned char* sp) const {
;     ...
;                     const int row = row0 + ai * 128 + m * 16; const float s = rsl[ai * 128 + m * 16];
;                     f32x4 v[2][2];
; #pragma unroll
;                     for (int bj = 0; bj < 2; ++bj)
; #pragma unroll
;                         for (int n = 0; n < 2; ++n) v[bj][n] = acc[ai][bj][m][n] * s;
;                     if (act == 3) {
;                         float q = 0.f;
; #pragma unroll
;                         for (int bj = 0; bj < 2; ++bj)
; #pragma unroll
;                             for (int n = 0; n < 2; ++n) q += (v[bj][n][0] * v[bj][n][0] + v[bj][n][1] * v[bj][n][1]) + (v[bj][n][2] * v[bj][n][2] + v[bj][n][3] * v[bj][n][3]);
;                         q += __shfl_xor(q, 16); q += __shfl_xor(q, 32);
;                         const float ri = rsqrtf(q * (1.f / 64.f) + EPS) * osc;
; #pragma unroll
;                         for (int bj = 0; bj < 2; ++bj)
; #pragma unroll
;                             for (int n = 0; n < 2; ++n) { const f32x4 g = *(const f32x4*)(gn + 32 * bj + 8 * fq + 4 * n); v[bj][n] = v[bj][n] * g * ri; }
.LBB0_375:
	s_andn2_b64 vcc, exec, s[64:65]
	s_cbranch_vccnz .LBB0_377
	v_pk_mul_f32 v[18:19], v[42:43], v[42:43]
	v_pk_mul_f32 v[20:21], v[44:45], v[44:45]
	v_mul_f32_e32 v0, v40, v40
	v_pk_mov_b32 v[22:23], v[20:21], v[18:19] op_sel:[1,0]
	v_mov_b32_e32 v21, v19
	v_pk_add_f32 v[18:19], v[22:23], v[20:21]
	v_pk_mul_f32 v[20:21], v[46:47], v[46:47]
	v_pk_mul_f32 v[22:23], v[48:49], v[48:49]
	v_pk_add_f32 v[18:19], v[18:19], v[18:19] op_sel_hi:[0,1]
	v_pk_mov_b32 v[24:25], v[22:23], v[20:21] op_sel:[1,0]
	v_mov_b32_e32 v23, v21
	v_pk_add_f32 v[20:21], v[24:25], v[22:23]
	v_pk_fma_f32 v[22:23], v[40:41], v[40:41], v[0:1] op_sel_hi:[1,1,0]
	v_mul_f32_e32 v0, v38, v38
	v_pk_add_f32 v[20:21], v[20:21], v[20:21] op_sel_hi:[0,1]
	v_pk_fma_f32 v[24:25], v[38:39], v[38:39], v[0:1] op_sel_hi:[1,1,0]
	v_mul_f32_e32 v22, v36, v36
	v_mul_f32_e32 v24, v37, v37
	v_mul_f32_e32 v18, v34, v34
	v_mul_f32_e32 v20, v35, v35
	v_pk_add_f32 v[22:23], v[22:23], v[24:25]
	v_pk_add_f32 v[18:19], v[18:19], v[20:21]
	s_nop 0
	v_pk_add_f32 v[18:19], v[22:23], v[18:19]
	s_nop 0
	v_add_f32_e32 v0, v18, v19
	v_and_b32_e32 v19, 64, v187
	v_xor_b32_e32 v18, 16, v187
	v_add_u32_e32 v19, 64, v19
	v_cmp_lt_i32_e32 vcc, v18, v19
	s_nop 1
	v_cndmask_b32_e32 v18, v187, v18, vcc
	v_lshlrev_b32_e32 v18, 2, v18
	ds_bpermute_b32 v18, v18, v0
	s_waitcnt lgkmcnt(0)
	v_add_f32_e32 v0, v0, v18
	v_xor_b32_e32 v18, 32, v187
	v_cmp_lt_i32_e32 vcc, v18, v19
	s_nop 1
	v_cndmask_b32_e32 v18, v187, v18, vcc
	v_lshlrev_b32_e32 v18, 2, v18
	ds_bpermute_b32 v18, v18, v0
	s_waitcnt lgkmcnt(0)
	v_add_f32_e32 v0, v0, v18
	v_fmamk_f32 v0, v0, 0x3c800000, v184
	v_cmp_gt_f32_e32 vcc, s74, v0
	v_mul_f32_e32 v18, 0x4b800000, v0
	s_nop 0
	v_cndmask_b32_e32 v0, v0, v18, vcc
	v_rsq_f32_e32 v0, v0
	s_nop 0
	v_mul_f32_e32 v18, 0x45800000, v0
	v_cndmask_b32_e32 v0, v0, v18, vcc
	v_mul_f32_e32 v0, v164, v0
	v_pk_mul_f32 v[24:25], v[46:47], v[214:215]
	v_pk_mul_f32 v[20:21], v[42:43], v[210:211]
	v_pk_mul_f32 v[18:19], v[44:45], v[208:209]
	v_pk_mul_f32 v[22:23], v[48:49], v[212:213]
	v_pk_mul_f32 v[32:33], v[38:39], v[218:219]
	v_pk_mul_f32 v[30:31], v[40:41], v[216:217]
	v_pk_mul_f32 v[28:29], v[34:35], v[222:223]
	v_pk_mul_f32 v[26:27], v[36:37], v[220:221]
	v_pk_mul_f32 v[20:21], v[20:21], v[0:1] op_sel_hi:[1,0]
	v_pk_mul_f32 v[18:19], v[18:19], v[0:1] op_sel_hi:[1,0]
	v_pk_mul_f32 v[24:25], v[24:25], v[0:1] op_sel_hi:[1,0]
	v_pk_mul_f32 v[22:23], v[22:23], v[0:1] op_sel_hi:[1,0]
	v_pk_mul_f32 v[32:33], v[32:33], v[0:1] op_sel_hi:[1,0]
	v_pk_mul_f32 v[30:31], v[30:31], v[0:1] op_sel_hi:[1,0]
	v_pk_mul_f32 v[28:29], v[28:29], v[0:1] op_sel_hi:[1,0]
	v_pk_mul_f32 v[26:27], v[26:27], v[0:1] op_sel_hi:[1,0]

;     __device__ __forceinline__ void operator()(const f32x4 (&acc)[2][2][4][2], const pg8::Unit& u, int wr, int wc, int fr, int fq, LAS unsigned char* sp) const {
;     ...
;                     const int row = row0 + ai * 128 + m * 16; const float s = rsl[ai * 128 + m * 16];
;                     f32x4 v[2][2];
; #pragma unroll
;                     for (int bj = 0; bj < 2; ++bj)
; #pragma unroll
;                         for (int n = 0; n < 2; ++n) v[bj][n] = acc[ai][bj][m][n] * s;
;                     if (act == 3) {
;                         float q = 0.f;
; #pragma unroll
;                         for (int bj = 0; bj < 2; ++bj)
; #pragma unroll
;                             for (int n = 0; n < 2; ++n) q += (v[bj][n][0] * v[bj][n][0] + v[bj][n][1] * v[bj][n][1]) + (v[bj][n][2] * v[bj][n][2] + v[bj][n][3] * v[bj][n][3]);
;                         q += __shfl_xor(q, 16); q += __shfl_xor(q, 32);
;                         const float ri = rsqrtf(q * (1.f / 64.f) + EPS) * osc;
; #pragma unroll
;                         for (int bj = 0; bj < 2; ++bj)
; #pragma unroll
;                             for (int n = 0; n < 2; ++n) { const f32x4 g = *(const f32x4*)(gn + 32 * bj + 8 * fq + 4 * n); v[bj][n] = v[bj][n] * g * ri; }
.LBB0_379:
	s_andn2_b64 vcc, exec, s[8:9]
	s_cbranch_vccnz .LBB0_381
	v_pk_mul_f32 v[2:3], v[26:27], v[26:27]
	v_pk_mul_f32 v[4:5], v[28:29], v[28:29]
	v_mul_f32_e32 v0, v24, v24
	v_pk_mov_b32 v[6:7], v[4:5], v[2:3] op_sel:[1,0]
	v_mov_b32_e32 v5, v3
	v_pk_add_f32 v[2:3], v[6:7], v[4:5]
	v_pk_mul_f32 v[4:5], v[30:31], v[30:31]
	v_pk_mul_f32 v[6:7], v[32:33], v[32:33]
	v_pk_add_f32 v[2:3], v[2:3], v[2:3] op_sel_hi:[0,1]
	v_pk_mov_b32 v[8:9], v[6:7], v[4:5] op_sel:[1,0]
	v_mov_b32_e32 v7, v5
	v_pk_add_f32 v[4:5], v[8:9], v[6:7]
	v_pk_fma_f32 v[6:7], v[24:25], v[24:25], v[0:1] op_sel_hi:[1,1,0]
	v_mul_f32_e32 v0, v22, v22
	v_pk_add_f32 v[4:5], v[4:5], v[4:5] op_sel_hi:[0,1]
	v_pk_fma_f32 v[8:9], v[22:23], v[22:23], v[0:1] op_sel_hi:[1,1,0]
	v_mul_f32_e32 v6, v20, v20
	v_mul_f32_e32 v8, v21, v21
	v_mul_f32_e32 v2, v18, v18
	v_mul_f32_e32 v4, v19, v19
	v_pk_add_f32 v[6:7], v[6:7], v[8:9]
	v_pk_add_f32 v[2:3], v[2:3], v[4:5]
	s_nop 0
	v_pk_add_f32 v[2:3], v[6:7], v[2:3]
	s_nop 0
	v_add_f32_e32 v0, v2, v3
	v_and_b32_e32 v3, 64, v187
	v_xor_b32_e32 v2, 16, v187
	v_add_u32_e32 v3, 64, v3
	v_cmp_lt_i32_e32 vcc, v2, v3
	s_nop 1
	v_cndmask_b32_e32 v2, v187, v2, vcc
	v_lshlrev_b32_e32 v2, 2, v2
	ds_bpermute_b32 v2, v2, v0
	s_waitcnt lgkmcnt(0)
	v_add_f32_e32 v0, v0, v2
	v_xor_b32_e32 v2, 32, v187
	v_cmp_lt_i32_e32 vcc, v2, v3
	s_nop 1
	v_cndmask_b32_e32 v2, v187, v2, vcc
	v_lshlrev_b32_e32 v2, 2, v2
	ds_bpermute_b32 v2, v2, v0
	s_waitcnt lgkmcnt(0)
	v_add_f32_e32 v0, v0, v2
	v_fmamk_f32 v0, v0, 0x3c800000, v184
	v_cmp_gt_f32_e32 vcc, s74, v0
	v_mul_f32_e32 v2, 0x4b800000, v0
	s_nop 0
	v_cndmask_b32_e32 v0, v0, v2, vcc
	v_rsq_f32_e32 v0, v0
	s_nop 0
	v_mul_f32_e32 v2, 0x45800000, v0
	v_cndmask_b32_e32 v0, v0, v2, vcc
	v_mul_f32_e32 v0, v164, v0
	v_pk_mul_f32 v[8:9], v[30:31], v[214:215]
	v_pk_mul_f32 v[4:5], v[26:27], v[210:211]
	v_pk_mul_f32 v[2:3], v[28:29], v[208:209]
	v_pk_mul_f32 v[6:7], v[32:33], v[212:213]
	v_pk_mul_f32 v[16:17], v[22:23], v[218:219]
	v_pk_mul_f32 v[14:15], v[24:25], v[216:217]
	v_pk_mul_f32 v[12:13], v[18:19], v[222:223]
	v_pk_mul_f32 v[10:11], v[20:21], v[220:221]
	v_pk_mul_f32 v[4:5], v[4:5], v[0:1] op_sel_hi:[1,0]
	v_pk_mul_f32 v[2:3], v[2:3], v[0:1] op_sel_hi:[1,0]
	v_pk_mul_f32 v[8:9], v[8:9], v[0:1] op_sel_hi:[1,0]
	v_pk_mul_f32 v[6:7], v[6:7], v[0:1] op_sel_hi:[1,0]
	v_pk_mul_f32 v[16:17], v[16:17], v[0:1] op_sel_hi:[1,0]
	v_pk_mul_f32 v[14:15], v[14:15], v[0:1] op_sel_hi:[1,0]
	v_pk_mul_f32 v[12:13], v[12:13], v[0:1] op_sel_hi:[1,0]
	v_pk_mul_f32 v[10:11], v[10:11], v[0:1] op_sel_hi:[1,0]
